# stack10 + attention: P packs and loop bookkeeping moved before the step barrier (under the V-prefetch read latency), K reads first after the barrier
# baseline (speedup 1.0000x reference)
.Lat_first:
	s_mov_b32 s24, s30
	s_lshl_b32 s25, s11, 15
	s_add_i32 s25, s25, 0
	v_add_u32_e32 v64, s25, v248
	v_add_u32_e32 v65, v64, v244
	v_add_u32_e32 v66, v64, v245
	v_add_u32_e32 v67, v64, v246
	v_add_u32_e32 v64, v64, v247
	ds_read_b128 v[166:169], v65
	ds_read_b128 v[174:177], v65 offset:4096
	ds_read_b128 v[170:173], v66
	ds_read_b128 v[162:165], v66 offset:4096
	ds_read_b128 v[158:161], v67
	ds_read_b128 v[154:157], v67 offset:4096
	ds_read_b128 v[150:153], v64
	ds_read_b128 v[146:149], v64 offset:4096
	v_cmp_neq_f32_e64 s[36:37], 0, v209
	v_xor_b32_e32 v64, 0x80000000, v209
	s_branch .Lat_qk
.LBB1_522:
	s_mov_b32 s24, s30
	s_lshl_b32 s25, s11, 15
	s_add_i32 s25, s25, 0
	v_add_u32_e32 v64, s25, v248
	v_add_u32_e32 v65, v64, v244
	v_add_u32_e32 v66, v64, v245
	v_add_u32_e32 v67, v64, v246
	v_add_u32_e32 v64, v64, v247
	ds_read_b128 v[166:169], v65
	ds_read_b128 v[174:177], v65 offset:4096
	ds_read_b128 v[170:173], v66
	ds_read_b128 v[162:165], v66 offset:4096
	ds_read_b128 v[158:161], v67
	ds_read_b128 v[154:157], v67 offset:4096
	ds_read_b128 v[150:153], v64
	ds_read_b128 v[146:149], v64 offset:4096
	v_cmp_neq_f32_e64 s[36:37], 0, v209
	v_xor_b32_e32 v64, 0x80000000, v209
.Lat_qk:
	s_mov_b64 vcc, s[36:37]
	s_cbranch_vccz .LBB1_532
	s_lshl_b32 s25, s10, 15
	s_add_i32 s30, s25, s7
	s_mov_b32 s31, m0
	s_mov_b32 m0, s30
	s_nop 0
	global_load_lds_dwordx4 v[212:213], off
	s_mov_b32 m0, s31
	s_addk_i32 s30, 0x2000
	v_lshl_add_u64 v[66:67], v[212:213], 0, s[48:49]
	s_mov_b32 s31, m0
	s_mov_b32 m0, s30
	s_nop 0
	global_load_lds_dwordx4 v[66:67], off
	s_mov_b32 m0, s31
	v_lshl_add_u64 v[68:69], v[210:211], 0, s[26:27]
	s_add_i32 s25, s25, s9
	s_mov_b32 s30, m0
	s_mov_b32 m0, s25
	s_nop 0
	global_load_lds_dwordx4 v[68:69], off
	s_mov_b32 m0, s30
	s_addk_i32 s25, 0x2000
	s_mov_b64 s[30:31], 0x88000
	v_lshl_add_u64 v[70:71], v[68:69], 0, s[30:31]
	s_mov_b32 s30, m0
	s_mov_b32 m0, s25
	s_nop 0
	global_load_lds_dwordx4 v[70:71], off
	s_mov_b32 m0, s30
	s_lshl_b32 s25, s11, 15
	v_mov_b32_e32 v65, v64
	v_pk_mov_b32 v[66:67], v[64:65], v[64:65]
	v_pk_mov_b32 v[68:69], v[64:65], v[64:65]
	v_pk_mov_b32 v[70:71], v[64:65], v[64:65]
	v_pk_mov_b32 v[72:73], v[64:65], v[64:65]
	v_pk_mov_b32 v[74:75], v[64:65], v[64:65]
	v_pk_mov_b32 v[76:77], v[64:65], v[64:65]
	v_pk_mov_b32 v[78:79], v[64:65], v[64:65]
	s_waitcnt lgkmcnt(7)
	v_mfma_f32_32x32x16_bf16 v[80:95], v[166:169], v[126:129], v[64:79]
	s_waitcnt lgkmcnt(6)
	v_mfma_f32_32x32x16_bf16 v[96:111], v[174:177], v[126:129], v[64:79]
	s_waitcnt lgkmcnt(5)
	v_mfma_f32_32x32x16_bf16 v[80:95], v[170:173], v[122:125], v[80:95]
	s_waitcnt lgkmcnt(4)
	v_mfma_f32_32x32x16_bf16 v[96:111], v[162:165], v[122:125], v[96:111]
	s_waitcnt lgkmcnt(3)
	v_mfma_f32_32x32x16_bf16 v[80:95], v[158:161], v[118:121], v[80:95]
	s_waitcnt lgkmcnt(2)
	v_mfma_f32_32x32x16_bf16 v[96:111], v[154:157], v[118:121], v[96:111]
	s_waitcnt lgkmcnt(1)
	v_mfma_f32_32x32x16_bf16 v[80:95], v[150:153], v[114:117], v[80:95]
	s_waitcnt lgkmcnt(0)
	v_mfma_f32_32x32x16_bf16 v[96:111], v[146:149], v[114:117], v[96:111]
	s_cbranch_execnz .LBB1_525

.LBB1_530:
	v_add3_u32 v64, s25, v243, v224
	ds_read_b128 v[190:193], v64 offset:16384
	ds_read_b128 v[186:189], v64 offset:20480
	ds_read_b128 v[182:185], v64 offset:24576
	ds_read_b128 v[142:145], v64 offset:28672
	v_cvt_pk_bf16_f32 v178, v80, v81
	v_cvt_pk_bf16_f32 v179, v82, v83
	v_cvt_pk_bf16_f32 v180, v84, v85
	v_cvt_pk_bf16_f32 v181, v86, v87
	v_cvt_pk_bf16_f32 v138, v88, v89
	v_cvt_pk_bf16_f32 v139, v90, v91
	v_cvt_pk_bf16_f32 v140, v92, v93
	v_cvt_pk_bf16_f32 v141, v94, v95
	v_cvt_pk_bf16_f32 v134, v96, v97
	v_cvt_pk_bf16_f32 v135, v98, v99
	v_cvt_pk_bf16_f32 v136, v100, v101
	v_cvt_pk_bf16_f32 v137, v102, v103
	v_cvt_pk_bf16_f32 v130, v104, v105
	v_cvt_pk_bf16_f32 v131, v106, v107
	v_cvt_pk_bf16_f32 v132, v108, v109
	v_cvt_pk_bf16_f32 v133, v110, v111
	v_add_f32_e32 v238, v66, v238
	v_lshl_add_u64 v[212:213], v[212:213], 0, s[34:35]
	s_add_u32 s26, s26, 0x80
	s_addc_u32 s27, s27, 0
	s_waitcnt vmcnt(0) lgkmcnt(0)
	s_barrier
	s_cmpk_eq_i32 s26, 0x2100
	s_cbranch_scc1 .LBB1_534
	s_mov_b32 s30, s11
	s_mov_b32 s11, s10
	s_mov_b32 s10, s24
	s_branch .LBB1_522
